# silu-gate epilogue: write-through only when the unit is the last of its stream, write-back otherwise
# baseline (speedup 1.0000x reference)
.LBB0_972:
	s_and_b64 vcc, exec, s[4:5]
	s_cbranch_vccz .LBB0_974
	s_and_b64 s[4:5], s[22:23], exec
	s_mov_b64 s[4:5], s[0:1]
	s_cselect_b32 s6, -3, -6
	s_load_dwordx2 s[4:5], s[4:5], 0xd0
	s_add_i32 s6, s6, s74
	s_lshl_b32 s6, s6, 8
	s_ashr_i32 s7, s6, 31
	s_lshl_b64 s[6:7], s[6:7], 1
	s_waitcnt lgkmcnt(0)
	s_add_u32 s4, s4, s6
	v_lshlrev_b32_e32 v130, 3, v191
	s_addc_u32 s5, s5, s7
	v_ashrrev_i32_e32 v131, 31, v130
	v_readlane_b32 s6, v254, 45
	v_lshl_add_u64 v[130:131], v[130:131], 1, s[4:5]
	s_mov_b64 s[4:5], 0x6000000
	v_or_b32_e32 v112, s6, v189
	v_lshl_add_u64 v[130:131], v[130:131], 0, s[4:5]
	v_readlane_b32 s4, v254, 36
	s_cmp_eq_u32 s39, 3
	v_readlane_b32 s5, v254, 37
	v_lshl_add_u32 v132, s4, 8, v112
	v_ashrrev_i32_e32 v133, 31, v132
	v_mul_f32_e32 v112, 0xbfb8aa3b, v126
	v_lshlrev_b64 v[134:135], 11, v[132:133]
	v_exp_f32_e32 v112, v112
	v_mul_f32_e32 v133, 0xbfb8aa3b, v127
	v_exp_f32_e32 v133, v133
	v_lshl_add_u64 v[138:139], v[130:131], 0, v[134:135]
	v_add_f32_e32 v112, 1.0, v112
	v_rcp_f32_e32 v134, v112
	v_add_f32_e32 v112, 1.0, v133
	v_mul_f32_e32 v133, 0xbfb8aa3b, v128
	v_exp_f32_e32 v133, v133
	v_mul_f32_e32 v135, 0xbfb8aa3b, v129
	v_exp_f32_e32 v137, v135
	v_rcp_f32_e32 v135, v112
	v_add_f32_e32 v112, 1.0, v133
	v_mul_f32_e32 v133, 0xbfb8aa3b, v122
	v_rcp_f32_e32 v136, v112
	v_add_f32_e32 v112, 1.0, v137
	v_exp_f32_e32 v133, v133
	v_mul_f32_e32 v137, 0xbfb8aa3b, v123
	v_exp_f32_e32 v141, v137
	v_rcp_f32_e32 v137, v112
	v_add_f32_e32 v112, 1.0, v133
	v_mul_f32_e32 v133, 0xbfb8aa3b, v124
	v_rcp_f32_e32 v140, v112
	v_add_f32_e32 v112, 1.0, v141
	v_exp_f32_e32 v133, v133
	v_mul_f32_e32 v141, 0xbfb8aa3b, v125
	v_exp_f32_e32 v143, v141
	v_rcp_f32_e32 v141, v112
	v_add_f32_e32 v112, 1.0, v133
	v_rcp_f32_e32 v142, v112
	v_add_f32_e32 v112, 1.0, v143
	v_rcp_f32_e32 v143, v112
	v_mul_f32_e32 v112, 0xbfb8aa3b, v118
	v_exp_f32_e32 v112, v112
	v_mul_f32_e32 v133, 0xbfb8aa3b, v119
	v_readlane_b32 s4, v255, 29
	v_exp_f32_e32 v133, v133
	s_cselect_b32 s4, s19, s4
	v_readlane_b32 s5, v255, 28
	v_readlane_b32 s6, v255, 30
	v_pk_mul_f32 v[134:135], v[126:127], v[134:135]
	v_pk_mul_f32 v[136:137], v[128:129], v[136:137]
	v_pk_mul_f32 v[140:141], v[122:123], v[140:141]
	v_pk_mul_f32 v[142:143], v[124:125], v[142:143]
	s_cselect_b32 s6, s5, s6
	s_lshl_b32 s4, s4, 1
	s_mov_b32 s5, s15
	v_cvt_pk_bf16_f32 v134, v134, v135
	v_cvt_pk_bf16_f32 v135, v136, v137
	v_cvt_pk_bf16_f32 v136, v140, v141
	v_cvt_pk_bf16_f32 v137, v142, v143
	v_lshl_add_u64 v[140:141], v[138:139], 0, s[4:5]
	v_add_f32_e32 v112, 1.0, v112
	s_cmp_eq_u64 s[10:11], 0
	s_cbranch_scc1 .Lg_plain_0
	global_store_dwordx4 v[140:141], v[134:137], off sc1
	s_branch .Lg_done_0
.Lg_plain_0:
	global_store_dwordx4 v[140:141], v[134:137], off
.Lg_done_0:
	s_lshl_b32 s6, s6, 1
	s_mov_b32 s7, s15
	v_rcp_f32_e32 v134, v112
	v_add_f32_e32 v112, 1.0, v133
	v_mul_f32_e32 v133, 0xbfb8aa3b, v120
	v_exp_f32_e32 v133, v133
	v_mul_f32_e32 v135, 0xbfb8aa3b, v121
	v_exp_f32_e32 v137, v135
	v_rcp_f32_e32 v135, v112
	v_add_f32_e32 v112, 1.0, v133
	v_mul_f32_e32 v133, 0xbfb8aa3b, v114
	v_rcp_f32_e32 v136, v112
	v_add_f32_e32 v112, 1.0, v137
	v_exp_f32_e32 v133, v133
	v_mul_f32_e32 v137, 0xbfb8aa3b, v115
	v_exp_f32_e32 v141, v137
	v_rcp_f32_e32 v137, v112
	v_add_f32_e32 v112, 1.0, v133
	v_mul_f32_e32 v133, 0xbfb8aa3b, v116
	v_rcp_f32_e32 v140, v112
	v_add_f32_e32 v112, 1.0, v141
	v_exp_f32_e32 v133, v133
	v_mul_f32_e32 v141, 0xbfb8aa3b, v117
	v_exp_f32_e32 v143, v141
	v_rcp_f32_e32 v141, v112
	v_add_f32_e32 v112, 1.0, v133
	v_rcp_f32_e32 v142, v112
	v_add_f32_e32 v112, 1.0, v143
	v_rcp_f32_e32 v143, v112
	v_mul_f32_e32 v112, 0xbfb8aa3b, v108
	v_pk_mul_f32 v[134:135], v[118:119], v[134:135]
	v_pk_mul_f32 v[136:137], v[120:121], v[136:137]
	v_pk_mul_f32 v[140:141], v[114:115], v[140:141]
	v_pk_mul_f32 v[142:143], v[116:117], v[142:143]
	v_exp_f32_e32 v112, v112
	v_mul_f32_e32 v133, 0xbfb8aa3b, v109
	v_cvt_pk_bf16_f32 v134, v134, v135
	v_cvt_pk_bf16_f32 v135, v136, v137
	v_cvt_pk_bf16_f32 v136, v140, v141
	v_cvt_pk_bf16_f32 v137, v142, v143
	v_lshl_add_u64 v[138:139], v[138:139], 0, s[6:7]
	v_exp_f32_e32 v133, v133
	s_cmp_eq_u64 s[10:11], 0
	s_cbranch_scc1 .Lg_plain_1
	global_store_dwordx4 v[138:139], v[134:137], off sc1
	s_branch .Lg_done_1
.Lg_plain_1:
	global_store_dwordx4 v[138:139], v[134:137], off
.Lg_done_1:
	v_add_f32_e32 v112, 1.0, v112
	s_nop 0
	v_or_b32_e32 v134, 16, v132
	v_ashrrev_i32_e32 v135, 31, v134
	v_lshlrev_b64 v[134:135], 11, v[134:135]
	v_lshl_add_u64 v[138:139], v[130:131], 0, v[134:135]
	v_rcp_f32_e32 v134, v112
	v_add_f32_e32 v112, 1.0, v133
	v_mul_f32_e32 v133, 0xbfb8aa3b, v110
	v_exp_f32_e32 v133, v133
	v_mul_f32_e32 v135, 0xbfb8aa3b, v111
	v_exp_f32_e32 v137, v135
	v_rcp_f32_e32 v135, v112
	v_add_f32_e32 v112, 1.0, v133
	v_mul_f32_e32 v133, 0xbfb8aa3b, v104
	v_rcp_f32_e32 v136, v112
	v_add_f32_e32 v112, 1.0, v137
	v_exp_f32_e32 v133, v133
	v_mul_f32_e32 v137, 0xbfb8aa3b, v105
	v_exp_f32_e32 v141, v137
	v_rcp_f32_e32 v137, v112
	v_add_f32_e32 v112, 1.0, v133
	v_mul_f32_e32 v133, 0xbfb8aa3b, v106
	v_rcp_f32_e32 v140, v112
	v_add_f32_e32 v112, 1.0, v141
	v_exp_f32_e32 v133, v133
	v_mul_f32_e32 v141, 0xbfb8aa3b, v107
	v_exp_f32_e32 v143, v141
	v_rcp_f32_e32 v141, v112
	v_add_f32_e32 v112, 1.0, v133
	v_rcp_f32_e32 v142, v112
	v_add_f32_e32 v112, 1.0, v143
	v_rcp_f32_e32 v143, v112
	v_mul_f32_e32 v112, 0xbfb8aa3b, v100
	v_exp_f32_e32 v112, v112
	v_mul_f32_e32 v133, 0xbfb8aa3b, v101
	v_exp_f32_e32 v133, v133
	v_pk_mul_f32 v[134:135], v[108:109], v[134:135]
	v_pk_mul_f32 v[136:137], v[110:111], v[136:137]
	v_pk_mul_f32 v[140:141], v[104:105], v[140:141]
	v_pk_mul_f32 v[142:143], v[106:107], v[142:143]
	v_cvt_pk_bf16_f32 v134, v134, v135
	v_cvt_pk_bf16_f32 v135, v136, v137
	v_cvt_pk_bf16_f32 v136, v140, v141
	v_cvt_pk_bf16_f32 v137, v142, v143
	v_lshl_add_u64 v[140:141], v[138:139], 0, s[4:5]
	v_add_f32_e32 v112, 1.0, v112
	s_cmp_eq_u64 s[10:11], 0
	s_cbranch_scc1 .Lg_plain_2
	global_store_dwordx4 v[140:141], v[134:137], off sc1
	s_branch .Lg_done_2

.Lg_done_2:
	v_lshl_add_u64 v[138:139], v[138:139], 0, s[6:7]
	s_nop 0
	v_rcp_f32_e32 v134, v112
	v_add_f32_e32 v112, 1.0, v133
	v_mul_f32_e32 v133, 0xbfb8aa3b, v102
	v_exp_f32_e32 v133, v133
	v_mul_f32_e32 v135, 0xbfb8aa3b, v103
	v_exp_f32_e32 v137, v135
	v_rcp_f32_e32 v135, v112
	v_add_f32_e32 v112, 1.0, v133
	v_mul_f32_e32 v133, 0xbfb8aa3b, v96
	v_rcp_f32_e32 v136, v112
	v_add_f32_e32 v112, 1.0, v137
	v_exp_f32_e32 v133, v133
	v_mul_f32_e32 v137, 0xbfb8aa3b, v97
	v_exp_f32_e32 v141, v137
	v_rcp_f32_e32 v137, v112
	v_add_f32_e32 v112, 1.0, v133
	v_mul_f32_e32 v133, 0xbfb8aa3b, v98
	v_rcp_f32_e32 v140, v112
	v_add_f32_e32 v112, 1.0, v141
	v_exp_f32_e32 v133, v133
	v_mul_f32_e32 v141, 0xbfb8aa3b, v99
	v_exp_f32_e32 v143, v141
	v_rcp_f32_e32 v141, v112
	v_add_f32_e32 v112, 1.0, v133
	v_rcp_f32_e32 v142, v112
	v_add_f32_e32 v112, 1.0, v143
	v_rcp_f32_e32 v143, v112
	v_mul_f32_e32 v112, 0xbfb8aa3b, v92
	v_pk_mul_f32 v[134:135], v[100:101], v[134:135]
	v_pk_mul_f32 v[136:137], v[102:103], v[136:137]
	v_pk_mul_f32 v[140:141], v[96:97], v[140:141]
	v_pk_mul_f32 v[142:143], v[98:99], v[142:143]
	v_exp_f32_e32 v112, v112
	v_mul_f32_e32 v133, 0xbfb8aa3b, v93
	v_cvt_pk_bf16_f32 v134, v134, v135
	v_cvt_pk_bf16_f32 v135, v136, v137
	v_cvt_pk_bf16_f32 v136, v140, v141
	v_cvt_pk_bf16_f32 v137, v142, v143
	v_exp_f32_e32 v133, v133
	s_cmp_eq_u64 s[10:11], 0
	s_cbranch_scc1 .Lg_plain_3
	global_store_dwordx4 v[138:139], v[134:137], off sc1
	s_branch .Lg_done_3

.Lg_done_3:
	v_add_f32_e32 v112, 1.0, v112
	s_nop 0
	v_or_b32_e32 v134, 32, v132
	v_ashrrev_i32_e32 v135, 31, v134
	v_lshlrev_b64 v[134:135], 11, v[134:135]
	v_lshl_add_u64 v[138:139], v[130:131], 0, v[134:135]
	v_rcp_f32_e32 v134, v112
	v_add_f32_e32 v112, 1.0, v133
	v_mul_f32_e32 v133, 0xbfb8aa3b, v94
	v_exp_f32_e32 v133, v133
	v_mul_f32_e32 v135, 0xbfb8aa3b, v95
	v_exp_f32_e32 v137, v135
	v_rcp_f32_e32 v135, v112
	v_add_f32_e32 v112, 1.0, v133
	v_mul_f32_e32 v133, 0xbfb8aa3b, v88
	v_rcp_f32_e32 v136, v112
	v_add_f32_e32 v112, 1.0, v137
	v_exp_f32_e32 v133, v133
	v_mul_f32_e32 v137, 0xbfb8aa3b, v89
	v_exp_f32_e32 v141, v137
	v_rcp_f32_e32 v137, v112
	v_add_f32_e32 v112, 1.0, v133
	v_mul_f32_e32 v133, 0xbfb8aa3b, v90
	v_rcp_f32_e32 v140, v112
	v_add_f32_e32 v112, 1.0, v141
	v_exp_f32_e32 v133, v133
	v_mul_f32_e32 v141, 0xbfb8aa3b, v91
	v_exp_f32_e32 v143, v141
	v_rcp_f32_e32 v141, v112
	v_add_f32_e32 v112, 1.0, v133
	v_rcp_f32_e32 v142, v112
	v_add_f32_e32 v112, 1.0, v143
	v_rcp_f32_e32 v143, v112
	v_mul_f32_e32 v112, 0xbfb8aa3b, v84
	v_exp_f32_e32 v112, v112
	v_mul_f32_e32 v133, 0xbfb8aa3b, v85
	v_exp_f32_e32 v133, v133
	v_pk_mul_f32 v[134:135], v[92:93], v[134:135]
	v_pk_mul_f32 v[136:137], v[94:95], v[136:137]
	v_pk_mul_f32 v[140:141], v[88:89], v[140:141]
	v_pk_mul_f32 v[142:143], v[90:91], v[142:143]
	v_cvt_pk_bf16_f32 v134, v134, v135
	v_cvt_pk_bf16_f32 v135, v136, v137
	v_cvt_pk_bf16_f32 v136, v140, v141
	v_cvt_pk_bf16_f32 v137, v142, v143
	v_lshl_add_u64 v[140:141], v[138:139], 0, s[4:5]
	v_add_f32_e32 v112, 1.0, v112
	s_cmp_eq_u64 s[10:11], 0
	s_cbranch_scc1 .Lg_plain_4
	global_store_dwordx4 v[140:141], v[134:137], off sc1
	s_branch .Lg_done_4

.Lg_done_4:
	v_lshl_add_u64 v[138:139], v[138:139], 0, s[6:7]
	s_nop 0
	v_rcp_f32_e32 v134, v112
	v_add_f32_e32 v112, 1.0, v133
	v_mul_f32_e32 v133, 0xbfb8aa3b, v86
	v_exp_f32_e32 v133, v133
	v_mul_f32_e32 v135, 0xbfb8aa3b, v87
	v_exp_f32_e32 v137, v135
	v_rcp_f32_e32 v135, v112
	v_add_f32_e32 v112, 1.0, v133
	v_mul_f32_e32 v133, 0xbfb8aa3b, v80
	v_rcp_f32_e32 v136, v112
	v_add_f32_e32 v112, 1.0, v137
	v_exp_f32_e32 v133, v133
	v_mul_f32_e32 v137, 0xbfb8aa3b, v81
	v_exp_f32_e32 v141, v137
	v_rcp_f32_e32 v137, v112
	v_add_f32_e32 v112, 1.0, v133
	v_mul_f32_e32 v133, 0xbfb8aa3b, v82
	v_rcp_f32_e32 v140, v112
	v_add_f32_e32 v112, 1.0, v141
	v_exp_f32_e32 v133, v133
	v_mul_f32_e32 v141, 0xbfb8aa3b, v83
	v_exp_f32_e32 v143, v141
	v_rcp_f32_e32 v141, v112
	v_add_f32_e32 v112, 1.0, v133
	v_rcp_f32_e32 v142, v112
	v_add_f32_e32 v112, 1.0, v143
	v_rcp_f32_e32 v143, v112
	v_mul_f32_e32 v112, 0xbfb8aa3b, v76
	v_pk_mul_f32 v[134:135], v[84:85], v[134:135]
	v_pk_mul_f32 v[136:137], v[86:87], v[136:137]
	v_pk_mul_f32 v[140:141], v[80:81], v[140:141]
	v_pk_mul_f32 v[142:143], v[82:83], v[142:143]
	v_exp_f32_e32 v112, v112
	v_mul_f32_e32 v133, 0xbfb8aa3b, v77
	v_cvt_pk_bf16_f32 v134, v134, v135
	v_cvt_pk_bf16_f32 v135, v136, v137
	v_cvt_pk_bf16_f32 v136, v140, v141
	v_cvt_pk_bf16_f32 v137, v142, v143
	v_exp_f32_e32 v133, v133
	s_cmp_eq_u64 s[10:11], 0
	s_cbranch_scc1 .Lg_plain_5
	global_store_dwordx4 v[138:139], v[134:137], off sc1
	s_branch .Lg_done_5

.Lg_done_5:
	v_add_f32_e32 v112, 1.0, v112
	s_nop 0
	v_or_b32_e32 v134, 48, v132
	v_ashrrev_i32_e32 v135, 31, v134
	v_lshlrev_b64 v[134:135], 11, v[134:135]
	v_lshl_add_u64 v[138:139], v[130:131], 0, v[134:135]
	v_rcp_f32_e32 v134, v112
	v_add_f32_e32 v112, 1.0, v133
	v_mul_f32_e32 v133, 0xbfb8aa3b, v78
	v_exp_f32_e32 v133, v133
	v_mul_f32_e32 v135, 0xbfb8aa3b, v79
	v_exp_f32_e32 v137, v135
	v_rcp_f32_e32 v135, v112
	v_add_f32_e32 v112, 1.0, v133
	v_mul_f32_e32 v133, 0xbfb8aa3b, v72
	v_rcp_f32_e32 v136, v112
	v_add_f32_e32 v112, 1.0, v137
	v_exp_f32_e32 v133, v133
	v_mul_f32_e32 v137, 0xbfb8aa3b, v73
	v_exp_f32_e32 v141, v137
	v_rcp_f32_e32 v137, v112
	v_add_f32_e32 v112, 1.0, v133
	v_mul_f32_e32 v133, 0xbfb8aa3b, v74
	v_rcp_f32_e32 v140, v112
	v_add_f32_e32 v112, 1.0, v141
	v_exp_f32_e32 v133, v133
	v_mul_f32_e32 v141, 0xbfb8aa3b, v75
	v_exp_f32_e32 v143, v141
	v_rcp_f32_e32 v141, v112
	v_add_f32_e32 v112, 1.0, v133
	v_rcp_f32_e32 v142, v112
	v_add_f32_e32 v112, 1.0, v143
	v_rcp_f32_e32 v143, v112
	v_mul_f32_e32 v112, 0xbfb8aa3b, v68
	v_exp_f32_e32 v112, v112
	v_mul_f32_e32 v133, 0xbfb8aa3b, v69
	v_exp_f32_e32 v133, v133
	v_pk_mul_f32 v[134:135], v[76:77], v[134:135]
	v_pk_mul_f32 v[136:137], v[78:79], v[136:137]
	v_pk_mul_f32 v[140:141], v[72:73], v[140:141]
	v_pk_mul_f32 v[142:143], v[74:75], v[142:143]
	v_cvt_pk_bf16_f32 v134, v134, v135
	v_cvt_pk_bf16_f32 v135, v136, v137
	v_cvt_pk_bf16_f32 v136, v140, v141
	v_cvt_pk_bf16_f32 v137, v142, v143
	v_lshl_add_u64 v[140:141], v[138:139], 0, s[4:5]
	v_add_f32_e32 v112, 1.0, v112
	s_cmp_eq_u64 s[10:11], 0
	s_cbranch_scc1 .Lg_plain_6
	global_store_dwordx4 v[140:141], v[134:137], off sc1
	s_branch .Lg_done_6

.Lg_done_6:
	v_lshl_add_u64 v[138:139], v[138:139], 0, s[6:7]
	s_nop 0
	v_rcp_f32_e32 v134, v112
	v_add_f32_e32 v112, 1.0, v133
	v_mul_f32_e32 v133, 0xbfb8aa3b, v70
	v_exp_f32_e32 v133, v133
	v_mul_f32_e32 v135, 0xbfb8aa3b, v71
	v_exp_f32_e32 v137, v135
	v_rcp_f32_e32 v135, v112
	v_add_f32_e32 v112, 1.0, v133
	v_mul_f32_e32 v133, 0xbfb8aa3b, v64
	v_rcp_f32_e32 v136, v112
	v_add_f32_e32 v112, 1.0, v137
	v_exp_f32_e32 v133, v133
	v_mul_f32_e32 v137, 0xbfb8aa3b, v65
	v_exp_f32_e32 v141, v137
	v_rcp_f32_e32 v137, v112
	v_add_f32_e32 v112, 1.0, v133
	v_mul_f32_e32 v133, 0xbfb8aa3b, v66
	v_rcp_f32_e32 v140, v112
	v_add_f32_e32 v112, 1.0, v141
	v_exp_f32_e32 v133, v133
	v_mul_f32_e32 v141, 0xbfb8aa3b, v67
	v_exp_f32_e32 v143, v141
	v_rcp_f32_e32 v141, v112
	v_add_f32_e32 v112, 1.0, v133
	v_rcp_f32_e32 v142, v112
	v_add_f32_e32 v112, 1.0, v143
	v_rcp_f32_e32 v143, v112
	v_mul_f32_e32 v112, 0xbfb8aa3b, v60
	v_pk_mul_f32 v[134:135], v[68:69], v[134:135]
	v_pk_mul_f32 v[136:137], v[70:71], v[136:137]
	v_pk_mul_f32 v[140:141], v[64:65], v[140:141]
	v_pk_mul_f32 v[142:143], v[66:67], v[142:143]
	v_exp_f32_e32 v112, v112
	v_mul_f32_e32 v133, 0xbfb8aa3b, v61
	v_cvt_pk_bf16_f32 v134, v134, v135
	v_cvt_pk_bf16_f32 v135, v136, v137
	v_cvt_pk_bf16_f32 v136, v140, v141
	v_cvt_pk_bf16_f32 v137, v142, v143
	v_exp_f32_e32 v133, v133
	s_cmp_eq_u64 s[10:11], 0
	s_cbranch_scc1 .Lg_plain_7
	global_store_dwordx4 v[138:139], v[134:137], off sc1
	s_branch .Lg_done_7

.Lg_done_7:
	v_add_f32_e32 v112, 1.0, v112
	s_nop 0
	v_add_u32_e32 v134, 0x80, v132
	v_ashrrev_i32_e32 v135, 31, v134
	v_lshlrev_b64 v[134:135], 11, v[134:135]
	v_lshl_add_u64 v[138:139], v[130:131], 0, v[134:135]
	v_rcp_f32_e32 v134, v112
	v_add_f32_e32 v112, 1.0, v133
	v_mul_f32_e32 v133, 0xbfb8aa3b, v62
	v_exp_f32_e32 v133, v133
	v_mul_f32_e32 v135, 0xbfb8aa3b, v63
	v_exp_f32_e32 v137, v135
	v_rcp_f32_e32 v135, v112
	v_add_f32_e32 v112, 1.0, v133
	v_mul_f32_e32 v133, 0xbfb8aa3b, v56
	v_rcp_f32_e32 v136, v112
	v_add_f32_e32 v112, 1.0, v137
	v_exp_f32_e32 v133, v133
	v_mul_f32_e32 v137, 0xbfb8aa3b, v57
	v_exp_f32_e32 v141, v137
	v_rcp_f32_e32 v137, v112
	v_add_f32_e32 v112, 1.0, v133
	v_mul_f32_e32 v133, 0xbfb8aa3b, v58
	v_rcp_f32_e32 v140, v112
	v_add_f32_e32 v112, 1.0, v141
	v_exp_f32_e32 v133, v133
	v_mul_f32_e32 v141, 0xbfb8aa3b, v59
	v_exp_f32_e32 v143, v141
	v_rcp_f32_e32 v141, v112
	v_add_f32_e32 v112, 1.0, v133
	v_rcp_f32_e32 v142, v112
	v_add_f32_e32 v112, 1.0, v143
	v_rcp_f32_e32 v143, v112
	v_mul_f32_e32 v112, 0xbfb8aa3b, v52
	v_exp_f32_e32 v112, v112
	v_mul_f32_e32 v133, 0xbfb8aa3b, v53
	v_exp_f32_e32 v133, v133
	v_pk_mul_f32 v[134:135], v[60:61], v[134:135]
	v_pk_mul_f32 v[136:137], v[62:63], v[136:137]
	v_pk_mul_f32 v[140:141], v[56:57], v[140:141]
	v_pk_mul_f32 v[142:143], v[58:59], v[142:143]
	v_cvt_pk_bf16_f32 v134, v134, v135
	v_cvt_pk_bf16_f32 v135, v136, v137
	v_cvt_pk_bf16_f32 v136, v140, v141
	v_cvt_pk_bf16_f32 v137, v142, v143
	v_lshl_add_u64 v[140:141], v[138:139], 0, s[4:5]
	v_add_f32_e32 v112, 1.0, v112
	s_cmp_eq_u64 s[10:11], 0
	s_cbranch_scc1 .Lg_plain_8
	global_store_dwordx4 v[140:141], v[134:137], off sc1
	s_branch .Lg_done_8

.Lg_done_8:
	v_lshl_add_u64 v[138:139], v[138:139], 0, s[6:7]
	s_nop 0
	v_rcp_f32_e32 v134, v112
	v_add_f32_e32 v112, 1.0, v133
	v_mul_f32_e32 v133, 0xbfb8aa3b, v54
	v_exp_f32_e32 v133, v133
	v_mul_f32_e32 v135, 0xbfb8aa3b, v55
	v_exp_f32_e32 v137, v135
	v_rcp_f32_e32 v135, v112
	v_add_f32_e32 v112, 1.0, v133
	v_mul_f32_e32 v133, 0xbfb8aa3b, v48
	v_rcp_f32_e32 v136, v112
	v_add_f32_e32 v112, 1.0, v137
	v_exp_f32_e32 v133, v133
	v_mul_f32_e32 v137, 0xbfb8aa3b, v49
	v_exp_f32_e32 v141, v137
	v_rcp_f32_e32 v137, v112
	v_add_f32_e32 v112, 1.0, v133
	v_mul_f32_e32 v133, 0xbfb8aa3b, v50
	v_rcp_f32_e32 v140, v112
	v_add_f32_e32 v112, 1.0, v141
	v_exp_f32_e32 v133, v133
	v_mul_f32_e32 v141, 0xbfb8aa3b, v51
	v_exp_f32_e32 v143, v141
	v_rcp_f32_e32 v141, v112
	v_add_f32_e32 v112, 1.0, v133
	v_rcp_f32_e32 v142, v112
	v_add_f32_e32 v112, 1.0, v143
	v_rcp_f32_e32 v143, v112
	v_mul_f32_e32 v112, 0xbfb8aa3b, v44
	v_pk_mul_f32 v[134:135], v[52:53], v[134:135]
	v_pk_mul_f32 v[136:137], v[54:55], v[136:137]
	v_pk_mul_f32 v[140:141], v[48:49], v[140:141]
	v_pk_mul_f32 v[142:143], v[50:51], v[142:143]
	v_exp_f32_e32 v112, v112
	v_mul_f32_e32 v133, 0xbfb8aa3b, v45
	v_cvt_pk_bf16_f32 v134, v134, v135
	v_cvt_pk_bf16_f32 v135, v136, v137
	v_cvt_pk_bf16_f32 v136, v140, v141
	v_cvt_pk_bf16_f32 v137, v142, v143
	v_exp_f32_e32 v133, v133
	s_cmp_eq_u64 s[10:11], 0
	s_cbranch_scc1 .Lg_plain_9
	global_store_dwordx4 v[138:139], v[134:137], off sc1
	s_branch .Lg_done_9

.Lg_done_9:
	v_add_f32_e32 v112, 1.0, v112
	s_nop 0
	v_add_u32_e32 v134, 0x90, v132
	v_ashrrev_i32_e32 v135, 31, v134
	v_lshlrev_b64 v[134:135], 11, v[134:135]
	v_lshl_add_u64 v[138:139], v[130:131], 0, v[134:135]
	v_rcp_f32_e32 v134, v112
	v_add_f32_e32 v112, 1.0, v133
	v_mul_f32_e32 v133, 0xbfb8aa3b, v46
	v_exp_f32_e32 v133, v133
	v_mul_f32_e32 v135, 0xbfb8aa3b, v47
	v_exp_f32_e32 v137, v135
	v_rcp_f32_e32 v135, v112
	v_add_f32_e32 v112, 1.0, v133
	v_mul_f32_e32 v133, 0xbfb8aa3b, v40
	v_rcp_f32_e32 v136, v112
	v_add_f32_e32 v112, 1.0, v137
	v_exp_f32_e32 v133, v133
	v_mul_f32_e32 v137, 0xbfb8aa3b, v41
	v_exp_f32_e32 v141, v137
	v_rcp_f32_e32 v137, v112
	v_add_f32_e32 v112, 1.0, v133
	v_mul_f32_e32 v133, 0xbfb8aa3b, v42
	v_rcp_f32_e32 v140, v112
	v_add_f32_e32 v112, 1.0, v141
	v_exp_f32_e32 v133, v133
	v_mul_f32_e32 v141, 0xbfb8aa3b, v43
	v_exp_f32_e32 v143, v141
	v_rcp_f32_e32 v141, v112
	v_add_f32_e32 v112, 1.0, v133
	v_rcp_f32_e32 v142, v112
	v_add_f32_e32 v112, 1.0, v143
	v_rcp_f32_e32 v143, v112
	v_mul_f32_e32 v112, 0xbfb8aa3b, v36
	v_exp_f32_e32 v112, v112
	v_mul_f32_e32 v133, 0xbfb8aa3b, v37
	v_exp_f32_e32 v133, v133
	v_pk_mul_f32 v[134:135], v[44:45], v[134:135]
	v_pk_mul_f32 v[136:137], v[46:47], v[136:137]
	v_pk_mul_f32 v[140:141], v[40:41], v[140:141]
	v_pk_mul_f32 v[142:143], v[42:43], v[142:143]
	v_cvt_pk_bf16_f32 v134, v134, v135
	v_cvt_pk_bf16_f32 v135, v136, v137
	v_cvt_pk_bf16_f32 v136, v140, v141
	v_cvt_pk_bf16_f32 v137, v142, v143
	v_lshl_add_u64 v[140:141], v[138:139], 0, s[4:5]
	v_add_f32_e32 v112, 1.0, v112
	s_cmp_eq_u64 s[10:11], 0
	s_cbranch_scc1 .Lg_plain_10
	global_store_dwordx4 v[140:141], v[134:137], off sc1
	s_branch .Lg_done_10

.Lg_done_10:
	v_lshl_add_u64 v[138:139], v[138:139], 0, s[6:7]
	s_nop 0
	v_rcp_f32_e32 v134, v112
	v_add_f32_e32 v112, 1.0, v133
	v_mul_f32_e32 v133, 0xbfb8aa3b, v38
	v_exp_f32_e32 v133, v133
	v_mul_f32_e32 v135, 0xbfb8aa3b, v39
	v_exp_f32_e32 v137, v135
	v_rcp_f32_e32 v135, v112
	v_add_f32_e32 v112, 1.0, v133
	v_mul_f32_e32 v133, 0xbfb8aa3b, v32
	v_rcp_f32_e32 v136, v112
	v_add_f32_e32 v112, 1.0, v137
	v_exp_f32_e32 v133, v133
	v_mul_f32_e32 v137, 0xbfb8aa3b, v33
	v_exp_f32_e32 v141, v137
	v_rcp_f32_e32 v137, v112
	v_add_f32_e32 v112, 1.0, v133
	v_mul_f32_e32 v133, 0xbfb8aa3b, v34
	v_rcp_f32_e32 v140, v112
	v_add_f32_e32 v112, 1.0, v141
	v_exp_f32_e32 v133, v133
	v_mul_f32_e32 v141, 0xbfb8aa3b, v35
	v_exp_f32_e32 v143, v141
	v_rcp_f32_e32 v141, v112
	v_add_f32_e32 v112, 1.0, v133
	v_rcp_f32_e32 v142, v112
	v_add_f32_e32 v112, 1.0, v143
	v_rcp_f32_e32 v143, v112
	v_mul_f32_e32 v112, 0xbfb8aa3b, v28
	v_pk_mul_f32 v[134:135], v[36:37], v[134:135]
	v_pk_mul_f32 v[136:137], v[38:39], v[136:137]
	v_pk_mul_f32 v[140:141], v[32:33], v[140:141]
	v_pk_mul_f32 v[142:143], v[34:35], v[142:143]
	v_exp_f32_e32 v112, v112
	v_mul_f32_e32 v133, 0xbfb8aa3b, v29
	v_cvt_pk_bf16_f32 v134, v134, v135
	v_cvt_pk_bf16_f32 v135, v136, v137
	v_cvt_pk_bf16_f32 v136, v140, v141
	v_cvt_pk_bf16_f32 v137, v142, v143
	v_exp_f32_e32 v133, v133
	s_cmp_eq_u64 s[10:11], 0
	s_cbranch_scc1 .Lg_plain_11
	global_store_dwordx4 v[138:139], v[134:137], off sc1
	s_branch .Lg_done_11

.Lg_done_11:
	v_add_f32_e32 v112, 1.0, v112
	s_nop 0
	v_add_u32_e32 v134, 0xa0, v132
	v_ashrrev_i32_e32 v135, 31, v134
	v_lshlrev_b64 v[134:135], 11, v[134:135]
	v_lshl_add_u64 v[138:139], v[130:131], 0, v[134:135]
	v_rcp_f32_e32 v134, v112
	v_add_f32_e32 v112, 1.0, v133
	v_mul_f32_e32 v133, 0xbfb8aa3b, v30
	v_exp_f32_e32 v133, v133
	v_mul_f32_e32 v135, 0xbfb8aa3b, v31
	v_exp_f32_e32 v137, v135
	v_rcp_f32_e32 v135, v112
	v_add_f32_e32 v112, 1.0, v133
	v_mul_f32_e32 v133, 0xbfb8aa3b, v24
	v_rcp_f32_e32 v136, v112
	v_add_f32_e32 v112, 1.0, v137
	v_exp_f32_e32 v133, v133
	v_mul_f32_e32 v137, 0xbfb8aa3b, v25
	v_exp_f32_e32 v141, v137
	v_rcp_f32_e32 v137, v112
	v_add_f32_e32 v112, 1.0, v133
	v_mul_f32_e32 v133, 0xbfb8aa3b, v26
	v_rcp_f32_e32 v140, v112
	v_add_f32_e32 v112, 1.0, v141
	v_exp_f32_e32 v133, v133
	v_mul_f32_e32 v141, 0xbfb8aa3b, v27
	v_exp_f32_e32 v143, v141
	v_rcp_f32_e32 v141, v112
	v_add_f32_e32 v112, 1.0, v133
	v_rcp_f32_e32 v142, v112
	v_add_f32_e32 v112, 1.0, v143
	v_rcp_f32_e32 v143, v112
	v_mul_f32_e32 v112, 0xbfb8aa3b, v20
	v_exp_f32_e32 v112, v112
	v_mul_f32_e32 v133, 0xbfb8aa3b, v21
	v_exp_f32_e32 v133, v133
	v_pk_mul_f32 v[134:135], v[28:29], v[134:135]
	v_pk_mul_f32 v[136:137], v[30:31], v[136:137]
	v_pk_mul_f32 v[140:141], v[24:25], v[140:141]
	v_pk_mul_f32 v[142:143], v[26:27], v[142:143]
	v_cvt_pk_bf16_f32 v134, v134, v135
	v_cvt_pk_bf16_f32 v135, v136, v137
	v_cvt_pk_bf16_f32 v136, v140, v141
	v_cvt_pk_bf16_f32 v137, v142, v143
	v_lshl_add_u64 v[140:141], v[138:139], 0, s[4:5]
	v_add_f32_e32 v112, 1.0, v112
	s_cmp_eq_u64 s[10:11], 0
	s_cbranch_scc1 .Lg_plain_12
	global_store_dwordx4 v[140:141], v[134:137], off sc1
	s_branch .Lg_done_12

.Lg_done_12:
	v_add_u32_e32 v132, 0xb0, v132
	v_lshl_add_u64 v[138:139], v[138:139], 0, s[6:7]
	v_rcp_f32_e32 v134, v112
	v_add_f32_e32 v112, 1.0, v133
	v_mul_f32_e32 v133, 0xbfb8aa3b, v22
	v_exp_f32_e32 v133, v133
	v_mul_f32_e32 v135, 0xbfb8aa3b, v23
	v_exp_f32_e32 v137, v135
	v_rcp_f32_e32 v135, v112
	v_add_f32_e32 v112, 1.0, v133
	v_mul_f32_e32 v133, 0xbfb8aa3b, v16
	v_rcp_f32_e32 v136, v112
	v_add_f32_e32 v112, 1.0, v137
	v_exp_f32_e32 v133, v133
	v_mul_f32_e32 v137, 0xbfb8aa3b, v17
	v_exp_f32_e32 v141, v137
	v_rcp_f32_e32 v137, v112
	v_add_f32_e32 v112, 1.0, v133
	v_mul_f32_e32 v133, 0xbfb8aa3b, v18
	v_rcp_f32_e32 v140, v112
	v_add_f32_e32 v112, 1.0, v141
	v_exp_f32_e32 v133, v133
	v_mul_f32_e32 v141, 0xbfb8aa3b, v19
	v_exp_f32_e32 v143, v141
	v_rcp_f32_e32 v141, v112
	v_add_f32_e32 v112, 1.0, v133
	v_rcp_f32_e32 v142, v112
	v_add_f32_e32 v112, 1.0, v143
	v_rcp_f32_e32 v143, v112
	v_pk_mul_f32 v[134:135], v[20:21], v[134:135]
	v_pk_mul_f32 v[136:137], v[22:23], v[136:137]
	v_pk_mul_f32 v[140:141], v[16:17], v[140:141]
	v_pk_mul_f32 v[142:143], v[18:19], v[142:143]
	v_cvt_pk_bf16_f32 v134, v134, v135
	v_cvt_pk_bf16_f32 v135, v136, v137
	v_cvt_pk_bf16_f32 v136, v140, v141
	v_cvt_pk_bf16_f32 v137, v142, v143
	v_ashrrev_i32_e32 v133, 31, v132
	v_mul_f32_e32 v112, 0xbfb8aa3b, v12
	s_cmp_eq_u64 s[10:11], 0
	s_cbranch_scc1 .Lg_plain_13
	global_store_dwordx4 v[138:139], v[134:137], off sc1
	s_branch .Lg_done_13

.Lg_done_13:
	v_lshlrev_b64 v[132:133], 11, v[132:133]
	v_exp_f32_e32 v112, v112
	v_mul_f32_e32 v134, 0xbfb8aa3b, v13
	v_exp_f32_e32 v136, v134
	v_lshl_add_u64 v[134:135], v[130:131], 0, v[132:133]
	v_mul_f32_e32 v131, 0xbfb8aa3b, v14
	v_exp_f32_e32 v132, v131
	v_mul_f32_e32 v131, 0xbfb8aa3b, v15
	v_exp_f32_e32 v133, v131
	v_add_f32_e32 v112, 1.0, v112
	v_rcp_f32_e32 v130, v112
	v_add_f32_e32 v112, 1.0, v136
	v_rcp_f32_e32 v131, v112
	v_add_f32_e32 v112, 1.0, v132
	v_rcp_f32_e32 v132, v112
	v_add_f32_e32 v112, 1.0, v133
	v_mul_f32_e32 v133, 0xbfb8aa3b, v4
	v_exp_f32_e32 v136, v133
	v_mul_f32_e32 v133, 0xbfb8aa3b, v5
	v_exp_f32_e32 v137, v133
	v_rcp_f32_e32 v133, v112
	v_add_f32_e32 v112, 1.0, v136
	v_rcp_f32_e32 v136, v112
	v_add_f32_e32 v112, 1.0, v137
	v_mul_f32_e32 v137, 0xbfb8aa3b, v6
	v_exp_f32_e32 v138, v137
	v_mul_f32_e32 v137, 0xbfb8aa3b, v7
	v_exp_f32_e32 v139, v137
	v_rcp_f32_e32 v137, v112
	v_add_f32_e32 v112, 1.0, v138
	v_rcp_f32_e32 v138, v112
	v_add_f32_e32 v112, 1.0, v139
	v_rcp_f32_e32 v139, v112
	v_pk_mul_f32 v[130:131], v[12:13], v[130:131]
	v_pk_mul_f32 v[132:133], v[14:15], v[132:133]
	v_pk_mul_f32 v[136:137], v[4:5], v[136:137]
	v_pk_mul_f32 v[138:139], v[6:7], v[138:139]
	v_mul_f32_e32 v112, 0xbfb8aa3b, v8
	v_cvt_pk_bf16_f32 v130, v130, v131
	v_cvt_pk_bf16_f32 v131, v132, v133
	v_cvt_pk_bf16_f32 v132, v136, v137
	v_cvt_pk_bf16_f32 v133, v138, v139
	v_lshl_add_u64 v[136:137], v[134:135], 0, s[4:5]
	v_exp_f32_e32 v112, v112
	v_mul_f32_e32 v138, 0xbfb8aa3b, v9
	v_exp_f32_e32 v138, v138
	s_cmp_eq_u64 s[10:11], 0
	s_cbranch_scc1 .Lg_plain_14
	global_store_dwordx4 v[136:137], v[130:133], off sc1
	s_branch .Lg_done_14
.Lg_plain_14:
	global_store_dwordx4 v[136:137], v[130:133], off
.Lg_done_14:
	v_add_f32_e32 v112, 1.0, v112
	v_lshl_add_u64 v[134:135], v[134:135], 0, s[6:7]
	v_mul_f32_e32 v131, 0xbfb8aa3b, v10
	v_exp_f32_e32 v132, v131
	v_mul_f32_e32 v131, 0xbfb8aa3b, v11
	v_exp_f32_e32 v133, v131
	v_rcp_f32_e32 v130, v112
	v_add_f32_e32 v112, 1.0, v138
	v_rcp_f32_e32 v131, v112
	v_add_f32_e32 v112, 1.0, v132
	v_rcp_f32_e32 v132, v112
	v_add_f32_e32 v112, 1.0, v133
	v_mul_f32_e32 v133, 0xbfb8aa3b, v0
	v_exp_f32_e32 v136, v133
	v_mul_f32_e32 v133, 0xbfb8aa3b, v1
	v_exp_f32_e32 v137, v133
	v_rcp_f32_e32 v133, v112
	v_add_f32_e32 v112, 1.0, v136
	v_rcp_f32_e32 v136, v112
	v_add_f32_e32 v112, 1.0, v137
	v_mul_f32_e32 v137, 0xbfb8aa3b, v2
	v_exp_f32_e32 v138, v137
	v_mul_f32_e32 v137, 0xbfb8aa3b, v3
	v_exp_f32_e32 v139, v137
	v_rcp_f32_e32 v137, v112
	v_add_f32_e32 v112, 1.0, v138
	v_rcp_f32_e32 v138, v112
	v_add_f32_e32 v112, 1.0, v139
	v_rcp_f32_e32 v139, v112
	v_pk_mul_f32 v[130:131], v[8:9], v[130:131]
	v_pk_mul_f32 v[132:133], v[10:11], v[132:133]
	v_pk_mul_f32 v[136:137], v[0:1], v[136:137]
	v_pk_mul_f32 v[138:139], v[2:3], v[138:139]
	v_cvt_pk_bf16_f32 v130, v130, v131
	v_cvt_pk_bf16_f32 v131, v132, v133
	v_cvt_pk_bf16_f32 v132, v136, v137
	v_cvt_pk_bf16_f32 v133, v138, v139
	s_cmp_eq_u64 s[10:11], 0
	s_cbranch_scc1 .Lg_plain_15
	global_store_dwordx4 v[134:135], v[130:133], off sc1
	s_branch .Lg_done_15
.Lg_plain_15:
	global_store_dwordx4 v[134:135], v[130:133], off
.Lg_done_15:
.LBB0_974:
	s_cmp_lt_i32 s74, 3
	s_cselect_b64 s[4:5], -1, 0
	s_and_b64 s[4:5], s[22:23], s[4:5]
	s_andn2_b64 vcc, exec, s[4:5]
	s_cbranch_vccnz .LBB0_979
	s_waitcnt vmcnt(0)
	v_cmp_eq_u32_e32 vcc, 0, v187
	s_and_saveexec_b64 s[4:5], vcc
	s_cbranch_execz .LBB0_978
	s_mov_b64 s[6:7], exec
	v_mbcnt_lo_u32_b32 v112, s6, 0
	v_mbcnt_hi_u32_b32 v112, s7, v112
	v_cmp_eq_u32_e32 vcc, 0, v112
	s_and_b64 s[8:9], exec, vcc
	s_mov_b64 exec, s[8:9]
	s_cbranch_execz .LBB0_978
	v_readlane_b32 s8, v254, 36
	v_readlane_b32 s9, v254, 37
	s_lshl_b32 s8, s8, 6
	s_ashr_i32 s9, s8, 31
	s_lshl_b64 s[8:9], s[8:9], 2
	v_readlane_b32 s22, v254, 60
	v_readlane_b32 s23, v254, 61
	s_add_u32 s8, s22, s8
	s_addc_u32 s9, s23, s9
	s_bcnt1_i32_b64 s6, s[6:7]
	v_mov_b32_e32 v112, s6
	global_atomic_add v113, v112, s[8:9]
